# diff-attn: kvg1 waves issue next-tile LDS-DMA after QK MFMAs (TA de-congestion), first-tile DMA hoisted above Q waits, LDS flags via ds ops; EpiRes epilogues pipelined 16-deep
# speedup vs baseline: 1.0103x; 1.0103x over previous
; #define PRM(f) karg<decltype(Params::f)>((int)offsetof(Params, f))
; DI void diff_unit(unsigned char* smem, const bf16* __restrict__ QKV, bf16* __restrict__ Y, int h, int qb, float lam, float outscale, const float* __restrict__ gain, float kn0, float kn1, int tid) {
;     ...
;     const float slope = __uint_as_float((unsigned)(126 - h) << 23), s8 = __uint_as_float((unsigned)(129 - h) << 23);
;     const float slope2 = __uint_as_float(__builtin_amdgcn_readfirstlane(__float_as_uint(-slope * LOG2E))), c1 = 0.125f * LOG2E;
;     if (tid < 3) flag[tid] = 0u;
;     if (tid < 32) ((volatile float*)(smem + D3_CI))[tid] = s8 * (float)(32 * (tid >> 4) + (tid & 3) + 8 * ((tid & 15) >> 2));
; __global__ void __launch_bounds__(512, 2) mk_fwd(Params P) {
;     ...
;                     itemw[0] = w0; itemw[1] = w1;
;                 }
;                 __syncthreads();
;                 const unsigned w0 = itemw[0], old = itemw[1];
;                 if (w0 == 0xffffffffu) break;
;                 const int h = (int)(w0 & 0xffu), k = (int)(w0 >> 8);
;                 kcur = k;
;                 const unsigned ntop = old & 0xffffu, nbot = old >> 16;
;                 const float kn0 = __uint_as_float(__builtin_amdgcn_readfirstlane(__float_as_uint(sqrtf(kntab[h * 4 + 0] + kntab[h * 4 + 1]) * 1.004f)));
;                 const float kn1 = __uint_as_float(__builtin_amdgcn_readfirstlane(__float_as_uint(sqrtf(kntab[h * 4 + 2] + kntab[h * 4 + 3]) * 1.004f)));
;                 att::diff_unit(smem, QKV, Yb, h, k == 0 ? 127 - (int)ntop : (int)nbot, lam, 1.0f - li, PRM(subln) + l * 128, kn0, kn1, tid);
.LBB0_176:
	s_or_b64 exec, exec, s[8:9]
	s_mov_b64 s[4:5], src_shared_base
	s_add_i32 s4, 0, 0x20020
	s_cmp_lg_u32 s4, -1
	s_cselect_b32 s4, s4, 0
	s_cselect_b32 s8, s5, 0
	v_mov_b32_e32 v0, s4
	s_add_i32 s4, 0, 0x20024
	s_cmp_lg_u32 s4, -1
	v_mov_b32_e32 v1, s8
	s_cselect_b32 s4, s4, 0
	s_cselect_b32 s5, s5, 0
	ds_write_b32 v0, v3
	s_waitcnt vmcnt(0)
	v_mov_b32_e32 v0, s4
	v_mov_b32_e32 v1, s5
	ds_write_b32 v0, v2
	s_waitcnt vmcnt(0)
.LBB0_177:
	s_or_b64 exec, exec, s[6:7]
	s_add_i32 s51, 0, 0x20020
	s_cmp_lg_u32 s51, -1
	s_cselect_b32 s4, s51, 0
	s_cselect_b32 s5, s41, 0
	v_mov_b32_e32 v0, s4
	s_add_i32 s4, 0, 0x20024
	s_cmp_lg_u32 s4, -1
	v_mov_b32_e32 v1, s5
	s_cselect_b32 s4, s4, 0
	s_cselect_b32 s5, s41, 0
	s_waitcnt lgkmcnt(0)
	s_barrier
	ds_read_b32 v164, v0
	s_waitcnt vmcnt(0)
	v_mov_b32_e32 v0, s4
	v_mov_b32_e32 v1, s5
	ds_read_b32 v0, v0
	s_waitcnt vmcnt(0) lgkmcnt(0)
	v_cmp_ne_u32_e32 vcc, -1, v164
	v_cmp_eq_u32_e64 s[4:5], -1, v164
	s_and_saveexec_b64 s[24:25], vcc
	s_cbranch_execz .LBB0_166
	v_and_b32_e32 v82, 0xff, v164
	v_readlane_b32 s6, v252, 44
	v_mov_b32_e32 v3, s41
	v_mov_b32_e32 v5, s41
	v_lshl_add_u32 v2, v82, 4, s6
	v_add_u32_e32 v4, 4, v2
	ds_read_b32 v1, v2
	s_waitcnt vmcnt(0)
	s_mov_b64 s[8:9], s[0:1]
	ds_read_b32 v4, v4
	s_waitcnt vmcnt(0)
	v_mov_b32_e32 v83, v148
	s_waitcnt lgkmcnt(0)
	v_add_f32_e32 v1, v1, v4
	v_cmp_gt_f32_e32 vcc, s83, v1
	v_mul_f32_e32 v4, 0x4f800000, v1
	s_nop 0
	v_cndmask_b32_e32 v1, v1, v4, vcc
	v_sqrt_f32_e32 v4, v1
	s_nop 0
	v_add_u32_e32 v5, -1, v4
	v_fma_f32 v6, -v5, v4, v1
	v_cmp_ge_f32_e64 s[6:7], 0, v6
	v_add_u32_e32 v6, 1, v4
	s_nop 0
	v_cndmask_b32_e64 v5, v4, v5, s[6:7]
	v_fma_f32 v4, -v6, v4, v1
	v_cmp_lt_f32_e64 s[6:7], 0, v4
	s_nop 1
	v_cndmask_b32_e64 v4, v5, v6, s[6:7]
	v_mul_f32_e32 v5, 0x37800000, v4
	v_cndmask_b32_e32 v4, v4, v5, vcc
	v_cmp_class_f32_e32 vcc, v1, v203
	v_mov_b32_e32 v5, s41
	s_nop 0
	v_cndmask_b32_e32 v1, v4, v1, vcc
	v_add_u32_e32 v4, 8, v2
	v_add_u32_e32 v2, 12, v2
	v_readfirstlane_b32 s14, v1
	ds_read_b32 v1, v4
	s_waitcnt vmcnt(0)
	ds_read_b32 v2, v2
	s_waitcnt vmcnt(0) lgkmcnt(0)
	v_add_f32_e32 v1, v1, v2
	v_cmp_gt_f32_e32 vcc, s83, v1
	v_mul_f32_e32 v2, 0x4f800000, v1
	s_nop 0
	v_cndmask_b32_e32 v1, v1, v2, vcc
	v_sqrt_f32_e32 v2, v1
	s_nop 0
	v_add_u32_e32 v3, -1, v2
	v_fma_f32 v4, -v3, v2, v1
	v_cmp_ge_f32_e64 s[6:7], 0, v4
	v_add_u32_e32 v4, 1, v2
	s_nop 0
	v_cndmask_b32_e64 v3, v2, v3, s[6:7]
	v_fma_f32 v2, -v4, v2, v1
	v_cmp_lt_f32_e64 s[6:7], 0, v2
	s_nop 1
	v_cndmask_b32_e64 v2, v3, v4, s[6:7]
	s_mov_b64 s[6:7], s[0:1]
	s_load_dwordx2 s[6:7], s[6:7], 0xa0
	s_load_dwordx2 s[28:29], s[8:9], 0xa0
	s_mov_b64 s[8:9], s[0:1]
	v_mul_f32_e32 v3, 0x37800000, v2
	s_load_dwordx2 s[30:31], s[8:9], 0x38
	v_cndmask_b32_e32 v2, v2, v3, vcc
	v_cmp_class_f32_e32 vcc, v1, v203
	s_nop 0
	v_readfirstlane_b32 s59, v83
	v_cndmask_b32_e32 v1, v2, v1, vcc
	v_cmp_gt_i32_e32 vcc, 3, v83
	v_readfirstlane_b32 s15, v1
	v_lshlrev_b32_e32 v1, 23, v82
	s_nop 0
	v_readfirstlane_b32 s16, v1
	s_and_saveexec_b64 s[8:9], vcc
	s_cbranch_execz .LBB0_180
	v_readlane_b32 s10, v252, 45
	v_mov_b32_e32 v3, s41
	s_nop 0
	v_lshl_add_u32 v2, v83, 2, s10
	ds_write_b32 v2, v33
	s_waitcnt vmcnt(0)
.LBB0_180:
	s_or_b64 exec, exec, s[8:9]
	v_sub_u32_e32 v152, 4.0, v1
	v_cmp_gt_i32_e32 vcc, 32, v83
	s_and_saveexec_b64 s[8:9], vcc
	s_cbranch_execz .LBB0_182
	v_lshlrev_b32_e32 v1, 1, v83
	v_and_b32_e32 v2, 3, v83
	v_and_or_b32 v1, v1, -8, v2
	v_cvt_f32_i32_e32 v1, v1
	v_readlane_b32 s10, v252, 46
	v_mov_b32_e32 v3, s41
	v_mul_f32_e32 v1, v152, v1
	v_lshl_add_u32 v2, v83, 2, s10
	ds_write_b32 v2, v1
	s_waitcnt vmcnt(0)
; __device__ __forceinline__ float sum_x32(float v) { auto rr = __builtin_amdgcn_permlane32_swap(__float_as_uint(v), __float_as_uint(v), false, false); return __uint_as_float(rr[0]) + __uint_as_float(rr[1]); }
; DI void diff_unit(unsigned char* smem, const bf16* __restrict__ QKV, bf16* __restrict__ Y, int h, int qb, float lam, float outscale, const float* __restrict__ gain, float kn0, float kn1, int tid) {
;     ...
;     bf16x8 qf[4];
;     { const bf16* qp = QKV + (size_t)qpos * NQKV + qcol + map * 64 + 8 * hi;
; #pragma unroll
;       for (int ds = 0; ds < 4; ++ds) qf[ds] = *(const bf16x8*)(qp + ds * 16); }
;     float qn = 0.f;
; #pragma unroll
;     for (int ds = 0; ds < 4; ++ds)
; #pragma unroll
;         for (int e = 0; e < 8; ++e) { const float qv = __uint_as_float(((unsigned)(unsigned short)qf[ds][e]) << 16); qn += qv * qv; }
;     qn = sum_x32(qn); qn = sqrtf(qn) * 1.0001f;
;     const float bq = c1 * qn * (map ? kn1 : kn0);
;     f32x16 o[4];
; #pragma unroll
;     for (int dt = 0; dt < 4; ++dt)
; #pragma unroll
;         for (int r = 0; r < 16; ++r) o[dt][r] = 0.f;
;     float m_run = -1e30f, l_run = 0.f;
;     bool dead = false;
;     const int drow = 4 * wq + (lane >> 4);
;     const bf16* ksrc = QKV + (size_t)drow * NQKV + kcol + (((lane & 15) ^ drow) * 8);
;     const bf16* vsrc = QKV + (size_t)drow * NQKV + vcol + (((lane & 15) ^ (4 * (lane >> 4))) * 8);
;     const int ddst = kvg * D3_GRP + 4 * wq * 256;
;     ...
;     int koff[4], voff[4];
;     { const int x = r32 & 15, bp = ((map << 3) | hi) ^ x;
; #pragma unroll
;       for (int ds = 0; ds < 4; ++ds) koff[ds] = kvg * D3_GRP + r32 * 256 + ((bp ^ (ds << 1)) << 4);
;       const int i = lane & 15, q = i >> 2, blk = (lane >> 4) & 1;
; #pragma unroll
;       for (int dt = 0; dt < 4; ++dt) voff[dt] = kvg * D3_GRP + D3_V + (4 * hi + q) * 256 + (2 * (dt ^ q) + blk) * 32 + (i & 3) * 8; }
;     int j = qb - kvg;
;     if (j >= 0) D3_DMA(j, 0);
.LBB0_182:
	s_or_b64 exec, exec, s[8:9]
	s_movk_i32 s8, 0x7f
	s_waitcnt lgkmcnt(0)
	s_add_u32 s6, s6, 0x1e900000
	v_cmp_gt_u32_e32 vcc, s85, v164
	v_sub_u32_sdwa v1, s8, v0 dst_sel:DWORD dst_unused:UNUSED_PAD src0_sel:DWORD src1_sel:WORD_0
	s_addc_u32 s7, s7, 0
	v_cndmask_b32_sdwa v166, v0, v1, vcc dst_sel:DWORD dst_unused:UNUSED_PAD src0_sel:WORD_1 src1_sel:DWORD
	s_bfe_u32 s60, s59, 0x10007
	v_and_b32_e32 v84, 31, v83
	v_lshlrev_b32_e32 v1, 6, v166
	s_lshl_b32 s42, s60, 5
	s_ashr_i32 s10, s59, 6
	v_or3_b32 v150, s42, v1, v84
	v_mov_b64_e32 v[2:3], s[6:7]
	s_and_b32 s62, s10, 1
	v_mad_i64_i32 v[2:3], s[8:9], v150, s44, v[2:3]
	v_lshlrev_b32_e32 v32, 8, v82
	v_bfe_u32 v0, v83, 5, 1
	v_lshl_add_u64 v[2:3], v[2:3], 0, v[32:33]
	s_lshl_b32 s68, s62, 7
	v_lshl_add_u64 v[2:3], v[2:3], 0, s[68:69]
	v_lshlrev_b32_e32 v4, 4, v0
	v_mov_b32_e32 v5, v33
	v_lshl_add_u64 v[2:3], v[2:3], 0, v[4:5]
	global_load_dwordx4 v[112:115], v[2:3], off
	global_load_dwordx4 v[116:119], v[2:3], off offset:32
	global_load_dwordx4 v[120:123], v[2:3], off offset:64
	global_load_dwordx4 v[124:127], v[2:3], off offset:96
	s_lshl_b32 s8, s10, 2
	s_and_b32 s8, s8, 12
	v_bfe_u32 v4, v83, 4, 2
	v_or_b32_e32 v3, s8, v4
	v_mul_u32_u24_e32 v3, 0x1800, v3
	v_lshlrev_b32_e32 v6, 1, v3
	v_mov_b32_e32 v7, v33
	v_and_b32_e32 v3, 15, v83
	v_lshl_add_u64 v[6:7], s[6:7], 0, v[6:7]
	v_bitop3_b32 v5, s8, v3, v4 bitop3:0x36
	v_lshl_add_u64 v[6:7], v[6:7], 0, v[32:33]
	v_lshlrev_b32_e32 v32, 4, v5
	v_lshlrev_b32_e32 v5, 6, v4
	v_lshlrev_b32_e32 v8, 4, v3
	s_ashr_i32 s61, s59, 8
	v_lshl_add_u64 v[154:155], v[6:7], 0, v[32:33]
	v_xor_b32_e32 v32, v8, v5
	s_lshl_b32 s17, s61, 15
	s_lshl_b32 s6, s8, 8
	v_lshl_add_u64 v[6:7], v[6:7], 0, v[32:33]
	s_mov_b64 s[8:9], 0x1000
	v_subrev_u32_e32 v85, s61, v166
	v_lshl_add_u64 v[156:157], v[6:7], 0, s[8:9]
	s_or_b32 s10, s6, s17
	v_cmp_lt_i32_e32 vcc, -1, v85
	s_nop 1
	s_and_saveexec_b64 s[6:7], vcc
	s_cbranch_execz .Lmy_dma0_skip
	v_mad_u64_u32 v[6:7], s[8:9], v85, s53, v[154:155]
	s_add_i32 s11, s10, 0
	v_mad_u64_u32 v[10:11], s[8:9], v85, s53, v[156:157]
	v_lshl_add_u64 v[8:9], v[6:7], 0, s[86:87]
	s_add_i32 s8, s11, 0x4000
	s_mov_b32 m0, s11
	s_nop 0
	global_load_lds_dwordx4 v[8:9], off
	s_mov_b32 m0, s8
	v_lshl_add_u64 v[8:9], v[6:7], 0, s[88:89]
	global_load_lds_dwordx4 v[10:11], off
	s_add_i32 m0, s11, 0x1000
	s_nop 0
	global_load_lds_dwordx4 v[8:9], off
	v_lshl_add_u64 v[8:9], v[10:11], 0, s[90:91]
	s_add_i32 m0, s11, 0x5000
	s_nop 0
	global_load_lds_dwordx4 v[8:9], off
	v_lshl_add_u64 v[8:9], v[6:7], 0, s[92:93]
	s_add_i32 m0, s11, 0x2000
	v_lshl_add_u64 v[6:7], v[6:7], 0, s[96:97]
	global_load_lds_dwordx4 v[8:9], off
	v_lshl_add_u64 v[8:9], v[10:11], 0, s[94:95]
	s_add_i32 m0, s11, 0x6000
	s_nop 0
	global_load_lds_dwordx4 v[8:9], off
	s_add_i32 m0, s11, 0x3000
	s_nop 0
	global_load_lds_dwordx4 v[6:7], off
	v_lshl_add_u64 v[6:7], v[10:11], 0, s[72:73]
	s_add_i32 m0, s11, 0x7000
	s_nop 0
	global_load_lds_dwordx4 v[6:7], off
.Lmy_dma0_join:
	s_or_b64 exec, exec, s[6:7]
	s_waitcnt vmcnt(11)
	v_and_b32_e32 v1, 0xffff0000, v112
	v_lshlrev_b32_e32 v2, 16, v112
	v_mul_f32_e32 v1, v1, v1
	v_fmac_f32_e32 v1, v2, v2
	v_lshlrev_b32_e32 v2, 16, v113
	v_fmac_f32_e32 v1, v2, v2
	v_and_b32_e32 v2, 0xffff0000, v113
	v_fmac_f32_e32 v1, v2, v2
	v_lshlrev_b32_e32 v2, 16, v114
	v_fmac_f32_e32 v1, v2, v2
	v_and_b32_e32 v2, 0xffff0000, v114
	v_fmac_f32_e32 v1, v2, v2
	v_lshlrev_b32_e32 v2, 16, v115
	v_fmac_f32_e32 v1, v2, v2
	v_and_b32_e32 v2, 0xffff0000, v115
	v_fmac_f32_e32 v1, v2, v2
	s_waitcnt vmcnt(10)
	v_lshlrev_b32_e32 v2, 16, v116
	v_fmac_f32_e32 v1, v2, v2
	v_and_b32_e32 v2, 0xffff0000, v116
	v_fmac_f32_e32 v1, v2, v2
	v_lshlrev_b32_e32 v2, 16, v117
	v_fmac_f32_e32 v1, v2, v2
	v_and_b32_e32 v2, 0xffff0000, v117
	v_fmac_f32_e32 v1, v2, v2
	v_lshlrev_b32_e32 v2, 16, v118
	v_fmac_f32_e32 v1, v2, v2
	v_and_b32_e32 v2, 0xffff0000, v118
	v_fmac_f32_e32 v1, v2, v2
	v_lshlrev_b32_e32 v2, 16, v119
	v_fmac_f32_e32 v1, v2, v2
	v_and_b32_e32 v2, 0xffff0000, v119
	v_fmac_f32_e32 v1, v2, v2
	s_waitcnt vmcnt(9)
	v_lshlrev_b32_e32 v2, 16, v120
	v_fmac_f32_e32 v1, v2, v2
	v_and_b32_e32 v2, 0xffff0000, v120
	v_fmac_f32_e32 v1, v2, v2
	v_lshlrev_b32_e32 v2, 16, v121
	v_fmac_f32_e32 v1, v2, v2
	v_and_b32_e32 v2, 0xffff0000, v121
	v_fmac_f32_e32 v1, v2, v2
	v_lshlrev_b32_e32 v2, 16, v122
	v_fmac_f32_e32 v1, v2, v2
	v_and_b32_e32 v2, 0xffff0000, v122
	v_fmac_f32_e32 v1, v2, v2
	v_lshlrev_b32_e32 v2, 16, v123
	v_fmac_f32_e32 v1, v2, v2
	v_and_b32_e32 v2, 0xffff0000, v123
	v_fmac_f32_e32 v1, v2, v2
	s_waitcnt vmcnt(8)
	v_lshlrev_b32_e32 v2, 16, v124
	v_fmac_f32_e32 v1, v2, v2
	v_and_b32_e32 v2, 0xffff0000, v124
	v_fmac_f32_e32 v1, v2, v2
	v_lshlrev_b32_e32 v2, 16, v125
	v_fmac_f32_e32 v1, v2, v2
	v_and_b32_e32 v2, 0xffff0000, v125
	v_fmac_f32_e32 v1, v2, v2
	v_lshlrev_b32_e32 v2, 16, v126
	v_fmac_f32_e32 v1, v2, v2
	v_and_b32_e32 v2, 0xffff0000, v126
	v_fmac_f32_e32 v1, v2, v2
	v_lshlrev_b32_e32 v2, 16, v127
	v_fmac_f32_e32 v1, v2, v2
	v_and_b32_e32 v2, 0xffff0000, v127
	v_fmac_f32_e32 v1, v2, v2
	v_mov_b32_e32 v2, v1
	s_nop 1
	v_permlane32_swap_b32_e32 v1, v2
	s_waitcnt vmcnt(0)
	v_cmp_eq_u32_e64 s[6:7], 0, v83
	s_waitcnt vmcnt(0) lgkmcnt(0)
	s_barrier
	s_and_saveexec_b64 s[8:9], s[6:7]
	s_cbranch_execz .LBB0_186
	s_add_i32 s11, 0, 0x20044
	s_cmp_lg_u32 s11, -1
	s_cselect_b32 s11, s11, 0
	s_cselect_b32 s12, s41, 0
	v_mov_b32_e32 v6, s11
	v_mov_b32_e32 v7, s12
	ds_write_b32 v6, v218
	s_waitcnt vmcnt(0)

; __device__ __forceinline__ float sum_x32(float v) { auto rr = __builtin_amdgcn_permlane32_swap(__float_as_uint(v), __float_as_uint(v), false, false); return __uint_as_float(rr[0]) + __uint_as_float(rr[1]); }
; DI void diff_unit(unsigned char* smem, const bf16* __restrict__ QKV, bf16* __restrict__ Y, int h, int qb, float lam, float outscale, const float* __restrict__ gain, float kn0, float kn1, int tid) {
;     ...
;     float qn = 0.f;
; #pragma unroll
;     for (int ds = 0; ds < 4; ++ds)
; #pragma unroll
;         for (int e = 0; e < 8; ++e) { const float qv = __uint_as_float(((unsigned)(unsigned short)qf[ds][e]) << 16); qn += qv * qv; }
;     qn = sum_x32(qn); qn = sqrtf(qn) * 1.0001f;
;     ...
;     if (j >= 0) D3_DMA(j, 0);
.Lmy_dma0_skip:
	s_waitcnt vmcnt(0)
	s_branch .Lmy_dma0_join

; DI void diff_unit(unsigned char* smem, const bf16* __restrict__ QKV, bf16* __restrict__ Y, int h, int qb, float lam, float outscale, const float* __restrict__ gain, float kn0, float kn1, int tid) {
;     ...
;         const bool mine_next = (j - 2 >= 0);
;         if (mine_next) D3_DMA(j - 2, D3_BUF - bufo);
.LBB0_207:
	s_or_b64 exec, exec, s[12:13]
	s_and_b32 s45, s68, 0x10000
	v_cmp_gt_i32_e64 s[12:13], 4, v85
	v_cmp_lt_i32_e64 s[14:15], 3, v85
	s_cmp_lg_u32 s61, 0
	s_cbranch_scc1 .Lmy_dma_top_skip
	s_and_saveexec_b64 s[16:17], s[14:15]
	s_cbranch_execz .LBB0_209
	v_add_u32_e32 v38, -4, v85
	v_mad_u64_u32 v[34:35], s[54:55], v38, s53, v[154:155]
	s_sub_i32 s47, s63, s45
	v_mad_u64_u32 v[38:39], s[54:55], v38, s53, v[156:157]
	v_lshl_add_u64 v[36:37], v[34:35], 0, s[86:87]
	s_add_i32 m0, s47, 0x10000
	s_add_i32 s54, s47, 0x14000
	global_load_lds_dwordx4 v[36:37], off
	s_mov_b32 m0, s54
	v_lshl_add_u64 v[36:37], v[34:35], 0, s[88:89]
	global_load_lds_dwordx4 v[38:39], off
	s_add_i32 m0, s47, 0x11000
	s_nop 0
	global_load_lds_dwordx4 v[36:37], off
	v_lshl_add_u64 v[36:37], v[38:39], 0, s[90:91]
	s_add_i32 m0, s47, 0x15000
	s_nop 0
	global_load_lds_dwordx4 v[36:37], off
	v_lshl_add_u64 v[36:37], v[34:35], 0, s[92:93]
	s_add_i32 m0, s47, 0x12000
	v_lshl_add_u64 v[34:35], v[34:35], 0, s[96:97]
	global_load_lds_dwordx4 v[36:37], off
	v_lshl_add_u64 v[36:37], v[38:39], 0, s[94:95]
	s_add_i32 m0, s47, 0x16000
	s_nop 0
	global_load_lds_dwordx4 v[36:37], off
	s_add_i32 m0, s47, 0x13000
	s_nop 0
	global_load_lds_dwordx4 v[34:35], off
	v_lshl_add_u64 v[34:35], v[38:39], 0, s[72:73]
	s_add_i32 m0, s47, 0x17000
	s_nop 0
	global_load_lds_dwordx4 v[34:35], off

; #define MFMA32(a, b, c) __builtin_amdgcn_mfma_f32_32x32x16_bf16((a), (b), (c), 0, 0, 0)
; DI void diff_unit(unsigned char* smem, const bf16* __restrict__ QKV, bf16* __restrict__ Y, int h, int qb, float lam, float outscale, const float* __restrict__ gain, float kn0, float kn1, int tid) {
;     ...
;                 bf16x8 kf[8];
; #pragma unroll
;                 for (int kh = 0; kh < 2; ++kh)
; #pragma unroll
;                     for (int ds = 0; ds < 4; ++ds) kf[kh * 4 + ds] = *(const bf16x8*)(tb + koff[ds] + kh * 8192);
;                 if (j < qb) {
; #pragma unroll
;                     for (int kh = 0; kh < 2; ++kh) { int cio = D3_CI + kh * 64; asm volatile("" : "+v"(cio)); p[kh] = *(const f32x16*)(smem + cio); }
;                 } else {
; #pragma unroll
;                     for (int kh = 0; kh < 2; ++kh)
; #pragma unroll
;                         for (int r = 0; r < 16; ++r) p[kh][r] = 0.f;
;                 }
;                 __builtin_amdgcn_sched_barrier(0);
; #pragma unroll
;                 for (int ds = 0; ds < 4; ++ds)
; #pragma unroll
;                     for (int kh = 0; kh < 2; ++kh) p[kh] = MFMA32(kf[kh * 4 + ds], qf[ds], p[kh]);
;     ...
;                 const float k0 = -s8;
;                 const int dqi = qpos - kv0;
; #pragma unroll
;                 for (int kh = 0; kh < 2; ++kh)
; #pragma unroll
;                     for (int r = 0; r < 16; ++r) { const int di = dqi - (32 * kh + (r & 3) + 8 * (r >> 2)); p[kh][r] = p[kh][r] + k0 * (float)(di < 0 ? -di : di); }
.Lmy_dma_top_skip:
	v_cmp_lt_i32_e32 vcc, 1, v85
	s_xor_b64 s[16:17], s[38:39], -1
	s_and_b64 s[56:57], vcc, s[16:17]
	s_mov_b64 s[16:17], s[38:39]
	s_and_saveexec_b64 s[54:55], s[56:57]
	s_cbranch_execz .Lmy_dma_stub
	s_add_i32 s81, s45, 0
	v_add_u32_e32 v34, s81, v167
	v_add_u32_e32 v35, s81, v168
	v_add_u32_e32 v36, s81, v169
	v_add_u32_e32 v37, s81, v186
	ds_read_b128 v[140:143], v34
	ds_read_b128 v[144:147], v34 offset:8192
	ds_read_b128 v[136:139], v35
	ds_read_b128 v[132:135], v35 offset:8192
	ds_read_b128 v[128:131], v36
	ds_read_b128 v[42:45], v36 offset:8192
	ds_read_b128 v[38:41], v37
	ds_read_b128 v[34:37], v37 offset:8192
	v_mov_b32_e32 v80, 0
	v_cmp_ge_i32_e32 vcc, v192, v166
	v_cmp_lt_i32_e64 s[16:17], v192, v166
	v_mov_b32_e32 v81, v80
	v_mov_b32_e32 v82, v80
	v_mov_b32_e32 v83, v80
	v_mov_b32_e32 v84, v80
	v_mov_b32_e32 v85, v80
	v_mov_b32_e32 v86, v80
	v_mov_b32_e32 v87, v80
	v_mov_b32_e32 v88, v80
	v_mov_b32_e32 v89, v80
	v_mov_b32_e32 v90, v80
	v_mov_b32_e32 v91, v80
	v_mov_b32_e32 v92, v80
	v_mov_b32_e32 v93, v80
	v_mov_b32_e32 v94, v80
	v_mov_b32_e32 v95, v80
	v_mov_b32_e32 v96, v80
	v_mov_b32_e32 v97, v80
	v_mov_b32_e32 v98, v80
	v_mov_b32_e32 v99, v80
	v_mov_b32_e32 v100, v80
	v_mov_b32_e32 v101, v80
	v_mov_b32_e32 v102, v80
	v_mov_b32_e32 v103, v80
	v_mov_b32_e32 v104, v80
	v_mov_b32_e32 v105, v80
	v_mov_b32_e32 v106, v80
	v_mov_b32_e32 v107, v80
	v_mov_b32_e32 v108, v80
	v_mov_b32_e32 v109, v80
	v_mov_b32_e32 v110, v80
	v_mov_b32_e32 v111, v80
	s_and_saveexec_b64 s[56:57], s[16:17]
	s_cbranch_execz .LBB0_212
	v_mov_b32_e32 v80, 0x20080
	v_mov_b32_e32 v96, 0x200c0
	v_add_u32_e32 v92, 0, v80
	s_nop 0
	ds_read_b128 v[80:83], v92
	ds_read_b128 v[84:87], v92 offset:16
	ds_read_b128 v[88:91], v92 offset:32
	ds_read_b128 v[92:95], v92 offset:48
	s_nop 0
	v_add_u32_e32 v108, 0, v96
	ds_read_b128 v[96:99], v108
	ds_read_b128 v[100:103], v108 offset:16
	ds_read_b128 v[104:107], v108 offset:32
	ds_read_b128 v[108:111], v108 offset:48
.LBB0_212:
	s_or_b64 exec, exec, s[56:57]
	v_add_u32_e32 v159, v191, v190
	v_add_u32_e32 v161, 0xffffffbf, v159
	s_waitcnt lgkmcnt(0)
	v_mfma_f32_32x32x16_bf16 v[80:95], v[140:143], v[112:115], v[80:95]
	v_mfma_f32_32x32x16_bf16 v[96:111], v[144:147], v[112:115], v[96:111]
	v_mfma_f32_32x32x16_bf16 v[80:95], v[136:139], v[116:119], v[80:95]
	v_mfma_f32_32x32x16_bf16 v[96:111], v[132:135], v[116:119], v[96:111]
	v_mfma_f32_32x32x16_bf16 v[80:95], v[128:131], v[120:123], v[80:95]
	v_mfma_f32_32x32x16_bf16 v[96:111], v[42:45], v[120:123], v[96:111]
	v_mfma_f32_32x32x16_bf16 v[80:95], v[38:41], v[124:127], v[80:95]
	v_mfma_f32_32x32x16_bf16 v[96:111], v[34:37], v[124:127], v[96:111]
	s_cmp_eq_u32 s61, 0
	s_cbranch_scc1 .Lmy_dma_mid_skip
	s_cmp_eq_u64 s[14:15], 0
	s_cbranch_scc1 .Lmy_dma_mid_skip
	v_add_u32_e32 v214, -2, v192
	v_mul_lo_u32 v214, v214, s53
	v_mov_b32_e32 v215, 0
	s_sub_i32 s32, s63, s45
	v_lshl_add_u64 v[212:213], v[154:155], 0, v[214:215]
	v_lshl_add_u64 v[216:217], v[156:157], 0, v[214:215]
	v_lshl_add_u64 v[214:215], v[212:213], 0, s[86:87]
	s_add_i32 m0, s32, 0x10000
	s_nop 0
	global_load_lds_dwordx4 v[214:215], off
	s_add_i32 m0, s32, 0x14000
	v_lshl_add_u64 v[214:215], v[212:213], 0, s[88:89]
	global_load_lds_dwordx4 v[216:217], off
	s_add_i32 m0, s32, 0x11000
	s_nop 0
	global_load_lds_dwordx4 v[214:215], off
	v_lshl_add_u64 v[214:215], v[216:217], 0, s[90:91]
	s_add_i32 m0, s32, 0x15000
	s_nop 0
	global_load_lds_dwordx4 v[214:215], off
	v_lshl_add_u64 v[214:215], v[212:213], 0, s[92:93]
	s_add_i32 m0, s32, 0x12000
	v_lshl_add_u64 v[212:213], v[212:213], 0, s[96:97]
	global_load_lds_dwordx4 v[214:215], off
	v_lshl_add_u64 v[214:215], v[216:217], 0, s[94:95]
	s_add_i32 m0, s32, 0x16000
	s_nop 0
	global_load_lds_dwordx4 v[214:215], off
	s_add_i32 m0, s32, 0x13000
	s_nop 0
	global_load_lds_dwordx4 v[212:213], off
	v_lshl_add_u64 v[212:213], v[216:217], 0, s[72:73]
	s_add_i32 m0, s32, 0x17000
	s_nop 0
	global_load_lds_dwordx4 v[212:213], off
.Lmy_dma_mid_skip:
	s_and_saveexec_b64 s[16:17], vcc
	s_xor_b64 s[16:17], exec, s[16:17]
	s_cbranch_execz .LBB0_214
	v_add_u32_e32 v34, 0xffffffbe, v159
	v_sub_u32_e32 v35, 0x42, v159
	v_max_i32_e32 v34, v34, v35
	v_sub_u32_e32 v35, 0, v161
	v_max_i32_e32 v36, v161, v35
	v_cvt_f32_u32_e32 v35, v34
	v_cvt_f32_u32_e32 v34, v36
	v_sub_u32_e32 v36, 2, v161
	v_pk_fma_f32 v[80:81], v[152:153], v[34:35], v[80:81] neg_lo:[1,0,0] neg_hi:[1,0,0]
	v_add_u32_e32 v35, -2, v161
	v_add_u32_e32 v34, -3, v161
	v_max_i32_e32 v36, v35, v36
	v_sub_u32_e32 v35, 3, v161
	v_max_i32_e32 v34, v34, v35
	v_cvt_f32_u32_e32 v35, v34
	v_cvt_f32_u32_e32 v34, v36
	v_sub_u32_e32 v36, 8, v161
	v_pk_fma_f32 v[82:83], v[152:153], v[34:35], v[82:83] neg_lo:[1,0,0] neg_hi:[1,0,0]
	v_add_u32_e32 v35, -8, v161
	v_add_u32_e32 v34, -9, v161
	v_max_i32_e32 v36, v35, v36
	v_sub_u32_e32 v35, 9, v161
	v_max_i32_e32 v34, v34, v35
	v_cvt_f32_u32_e32 v35, v34
	v_cvt_f32_u32_e32 v34, v36
	v_sub_u32_e32 v36, 10, v161
	v_pk_fma_f32 v[84:85], v[152:153], v[34:35], v[84:85] neg_lo:[1,0,0] neg_hi:[1,0,0]
	v_add_u32_e32 v35, -10, v161
	v_add_u32_e32 v34, -11, v161
	v_max_i32_e32 v36, v35, v36
	v_sub_u32_e32 v35, 11, v161
	v_max_i32_e32 v34, v34, v35
	v_cvt_f32_u32_e32 v35, v34
	v_cvt_f32_u32_e32 v34, v36
	v_sub_u32_e32 v36, 16, v161
	v_pk_fma_f32 v[86:87], v[152:153], v[34:35], v[86:87] neg_lo:[1,0,0] neg_hi:[1,0,0]
	v_add_u32_e32 v35, -16, v161
	v_subrev_u32_e32 v34, 17, v161
	v_max_i32_e32 v36, v35, v36
	v_sub_u32_e32 v35, 17, v161
	v_max_i32_e32 v34, v34, v35
	v_cvt_f32_u32_e32 v35, v34
	v_cvt_f32_u32_e32 v34, v36
	v_sub_u32_e32 v36, 18, v161
	v_pk_fma_f32 v[88:89], v[152:153], v[34:35], v[88:89] neg_lo:[1,0,0] neg_hi:[1,0,0]
; __device__ __forceinline__ float max_x32(float v) { auto rr = __builtin_amdgcn_permlane32_swap(__float_as_uint(v), __float_as_uint(v), false, false); return __builtin_fmaxf(__uint_as_float(rr[0]), __uint_as_float(rr[1])); }
; DI void diff_unit(unsigned char* smem, const bf16* __restrict__ QKV, bf16* __restrict__ Y, int h, int qb, float lam, float outscale, const float* __restrict__ gain, float kn0, float kn1, int tid) {
;     ...
;                     for (int r = 0; r < 16; ++r) { const int di = dqi - (32 * kh + (r & 3) + 8 * (r >> 2)); p[kh][r] = p[kh][r] + k0 * (float)(di < 0 ? -di : di); }
;                 float mx = p[0][0];
; #pragma unroll
;                 for (int kh = 0; kh < 2; ++kh)
; #pragma unroll
;                     for (int r = 0; r < 16; ++r) mx = __builtin_fmaxf(mx, p[kh][r]);
;                 float tmax = mx * c1;
;                 tmax = max_x32(tmax);
;                 const float m_new = __builtin_fmaxf(m_run, tmax);
;                 const float alpha = __builtin_amdgcn_exp2f(m_run - m_new);
;                 l_run *= alpha;
; #pragma unroll
;                 for (int dt = 0; dt < 4; ++dt)
; #pragma unroll
;                     for (int r = 0; r < 16; ++r) o[dt][r] *= alpha;
;                 m_run = m_new;
;                 t = -m_run;
	v_subrev_u32_e32 v35, 18, v161
	v_subrev_u32_e32 v34, 19, v161
	v_max_i32_e32 v36, v35, v36
	v_sub_u32_e32 v35, 19, v161
	v_max_i32_e32 v34, v34, v35
	v_cvt_f32_u32_e32 v35, v34
	v_cvt_f32_u32_e32 v34, v36
	v_sub_u32_e32 v36, 24, v161
	v_pk_fma_f32 v[90:91], v[152:153], v[34:35], v[90:91] neg_lo:[1,0,0] neg_hi:[1,0,0]
	v_subrev_u32_e32 v35, 24, v161
	v_subrev_u32_e32 v34, 25, v161
	v_max_i32_e32 v36, v35, v36
	v_sub_u32_e32 v35, 25, v161
	v_max_i32_e32 v34, v34, v35
	v_cvt_f32_u32_e32 v35, v34
	v_cvt_f32_u32_e32 v34, v36
	v_sub_u32_e32 v36, 26, v161
	v_pk_fma_f32 v[92:93], v[152:153], v[34:35], v[92:93] neg_lo:[1,0,0] neg_hi:[1,0,0]
	v_subrev_u32_e32 v35, 26, v161
	v_subrev_u32_e32 v34, 27, v161
	v_max_i32_e32 v36, v35, v36
	v_sub_u32_e32 v35, 27, v161
	v_max_i32_e32 v34, v34, v35
	v_cvt_f32_u32_e32 v35, v34
	v_cvt_f32_u32_e32 v34, v36
	v_sub_u32_e32 v36, 32, v161
	v_pk_fma_f32 v[94:95], v[152:153], v[34:35], v[94:95] neg_lo:[1,0,0] neg_hi:[1,0,0]
	v_subrev_u32_e32 v35, 32, v161
	v_subrev_u32_e32 v34, 33, v161
	v_max_i32_e32 v36, v35, v36
	v_sub_u32_e32 v35, 33, v161
	v_max_i32_e32 v34, v34, v35
	v_cvt_f32_u32_e32 v35, v34
	v_cvt_f32_u32_e32 v34, v36
	v_sub_u32_e32 v36, 34, v161
	v_pk_fma_f32 v[96:97], v[152:153], v[34:35], v[96:97] neg_lo:[1,0,0] neg_hi:[1,0,0]
	v_subrev_u32_e32 v35, 34, v161
	v_subrev_u32_e32 v34, 35, v161
	v_max_i32_e32 v36, v35, v36
	v_sub_u32_e32 v35, 35, v161
	v_max_i32_e32 v34, v34, v35
	v_cvt_f32_u32_e32 v35, v34
	v_cvt_f32_u32_e32 v34, v36
	v_sub_u32_e32 v36, 40, v161
	v_pk_fma_f32 v[98:99], v[152:153], v[34:35], v[98:99] neg_lo:[1,0,0] neg_hi:[1,0,0]
	v_subrev_u32_e32 v35, 40, v161
	v_subrev_u32_e32 v34, 41, v161
	v_max_i32_e32 v36, v35, v36
	v_sub_u32_e32 v35, 41, v161
	v_max_i32_e32 v34, v34, v35
	v_cvt_f32_u32_e32 v35, v34
	v_cvt_f32_u32_e32 v34, v36
	v_sub_u32_e32 v36, 42, v161
	v_pk_fma_f32 v[100:101], v[152:153], v[34:35], v[100:101] neg_lo:[1,0,0] neg_hi:[1,0,0]
	v_subrev_u32_e32 v35, 42, v161
	v_subrev_u32_e32 v34, 43, v161
	v_max_i32_e32 v36, v35, v36
	v_sub_u32_e32 v35, 43, v161
	v_max_i32_e32 v34, v34, v35
	v_cvt_f32_u32_e32 v35, v34
	v_cvt_f32_u32_e32 v34, v36
	v_sub_u32_e32 v36, 48, v161
	v_pk_fma_f32 v[102:103], v[152:153], v[34:35], v[102:103] neg_lo:[1,0,0] neg_hi:[1,0,0]
	v_subrev_u32_e32 v35, 48, v161
	v_subrev_u32_e32 v34, 49, v161
	v_max_i32_e32 v36, v35, v36
	v_sub_u32_e32 v35, 49, v161
	v_max_i32_e32 v34, v34, v35
	v_cvt_f32_u32_e32 v35, v34
	v_cvt_f32_u32_e32 v34, v36
	v_sub_u32_e32 v36, 50, v161
	v_pk_fma_f32 v[104:105], v[152:153], v[34:35], v[104:105] neg_lo:[1,0,0] neg_hi:[1,0,0]
	v_subrev_u32_e32 v35, 50, v161
	v_subrev_u32_e32 v34, 51, v161
	v_max_i32_e32 v36, v35, v36
	v_sub_u32_e32 v35, 51, v161
	v_max_i32_e32 v34, v34, v35
	v_cvt_f32_u32_e32 v35, v34
	v_cvt_f32_u32_e32 v34, v36
	v_sub_u32_e32 v36, 56, v161
	v_pk_fma_f32 v[106:107], v[152:153], v[34:35], v[106:107] neg_lo:[1,0,0] neg_hi:[1,0,0]
	v_subrev_u32_e32 v35, 56, v161
	v_subrev_u32_e32 v34, 57, v161
	v_max_i32_e32 v36, v35, v36
	v_sub_u32_e32 v35, 57, v161
	v_max_i32_e32 v34, v34, v35
	v_cvt_f32_u32_e32 v35, v34
	v_cvt_f32_u32_e32 v34, v36
	v_sub_u32_e32 v36, 58, v161
	v_pk_fma_f32 v[108:109], v[152:153], v[34:35], v[108:109] neg_lo:[1,0,0] neg_hi:[1,0,0]
	v_subrev_u32_e32 v35, 58, v161
	v_subrev_u32_e32 v34, 59, v161
	v_max_i32_e32 v36, v35, v36
	v_sub_u32_e32 v35, 59, v161
	v_max_i32_e32 v34, v34, v35
	v_cvt_f32_u32_e32 v35, v34
	v_cvt_f32_u32_e32 v34, v36
	v_pk_fma_f32 v[110:111], v[152:153], v[34:35], v[110:111] neg_lo:[1,0,0] neg_hi:[1,0,0]
	v_max_f32_e32 v34, v80, v81
	v_max3_f32 v34, v34, v82, v83
	v_max3_f32 v34, v34, v84, v85
	v_max3_f32 v34, v34, v86, v87
	v_max3_f32 v34, v34, v88, v89
	v_max3_f32 v34, v34, v90, v91
	v_max3_f32 v34, v34, v92, v93
	v_max3_f32 v34, v34, v94, v95
	v_max3_f32 v34, v34, v96, v97
	v_max3_f32 v34, v34, v98, v99
	v_max3_f32 v34, v34, v100, v101
	v_max3_f32 v34, v34, v102, v103
	v_max3_f32 v34, v34, v104, v105
	v_max3_f32 v34, v34, v106, v107
	v_max3_f32 v34, v34, v108, v109
	v_max3_f32 v34, v34, v110, v111
	v_mul_f32_e32 v34, 0x3e38aa3b, v34
	v_mov_b32_e32 v35, v34
	s_nop 1
	v_permlane32_swap_b32_e32 v34, v35
	v_max3_f32 v159, v163, v34, v35
	v_sub_f32_e32 v34, v163, v159
	v_exp_f32_e32 v34, v34
	s_nop 0
	v_pk_mul_f32 v[78:79], v[78:79], v[34:35] op_sel_hi:[1,0]
	v_pk_mul_f32 v[76:77], v[76:77], v[34:35] op_sel_hi:[1,0]
	v_pk_mul_f32 v[74:75], v[74:75], v[34:35] op_sel_hi:[1,0]
	v_pk_mul_f32 v[72:73], v[72:73], v[34:35] op_sel_hi:[1,0]
	v_pk_mul_f32 v[70:71], v[70:71], v[34:35] op_sel_hi:[1,0]
	v_pk_mul_f32 v[68:69], v[68:69], v[34:35] op_sel_hi:[1,0]
	v_pk_mul_f32 v[66:67], v[66:67], v[34:35] op_sel_hi:[1,0]
	v_pk_mul_f32 v[64:65], v[64:65], v[34:35] op_sel_hi:[1,0]
	v_pk_mul_f32 v[62:63], v[62:63], v[34:35] op_sel_hi:[1,0]
	v_pk_mul_f32 v[60:61], v[60:61], v[34:35] op_sel_hi:[1,0]
	v_pk_mul_f32 v[58:59], v[58:59], v[34:35] op_sel_hi:[1,0]
	v_pk_mul_f32 v[56:57], v[56:57], v[34:35] op_sel_hi:[1,0]
	v_pk_mul_f32 v[54:55], v[54:55], v[34:35] op_sel_hi:[1,0]
	v_pk_mul_f32 v[52:53], v[52:53], v[34:35] op_sel_hi:[1,0]
	v_pk_mul_f32 v[50:51], v[50:51], v[34:35] op_sel_hi:[1,0]
	v_pk_mul_f32 v[48:49], v[48:49], v[34:35] op_sel_hi:[1,0]
	v_pk_mul_f32 v[30:31], v[30:31], v[34:35] op_sel_hi:[1,0]
	v_pk_mul_f32 v[28:29], v[28:29], v[34:35] op_sel_hi:[1,0]
	v_pk_mul_f32 v[26:27], v[26:27], v[34:35] op_sel_hi:[1,0]
	v_pk_mul_f32 v[24:25], v[24:25], v[34:35] op_sel_hi:[1,0]
	v_pk_mul_f32 v[22:23], v[22:23], v[34:35] op_sel_hi:[1,0]
	v_pk_mul_f32 v[20:21], v[20:21], v[34:35] op_sel_hi:[1,0]
	v_pk_mul_f32 v[18:19], v[18:19], v[34:35] op_sel_hi:[1,0]
	v_pk_mul_f32 v[16:17], v[16:17], v[34:35] op_sel_hi:[1,0]
	v_pk_mul_f32 v[14:15], v[14:15], v[34:35] op_sel_hi:[1,0]
	v_pk_mul_f32 v[12:13], v[12:13], v[34:35] op_sel_hi:[1,0]
	v_pk_mul_f32 v[10:11], v[10:11], v[34:35] op_sel_hi:[1,0]
	v_pk_mul_f32 v[8:9], v[8:9], v[34:35] op_sel_hi:[1,0]
	v_pk_mul_f32 v[6:7], v[6:7], v[34:35] op_sel_hi:[1,0]
	v_pk_mul_f32 v[4:5], v[4:5], v[34:35] op_sel_hi:[1,0]
	v_pk_mul_f32 v[2:3], v[2:3], v[34:35] op_sel_hi:[1,0]
	v_pk_mul_f32 v[0:1], v[0:1], v[34:35] op_sel_hi:[1,0]
	v_mul_f32_e32 v162, v162, v34
	v_xor_b32_e32 v34, 0x80000000, v159

; DI void diff_unit(unsigned char* smem, const bf16* __restrict__ QKV, bf16* __restrict__ Y, int h, int qb, float lam, float outscale, const float* __restrict__ gain, float kn0, float kn1, int tid) {
;     ...
;         const bool mine_next = (j - 2 >= 0);
;         if (mine_next) D3_DMA(j - 2, D3_BUF - bufo);
.Lmy_dma_stub:
	s_cmp_eq_u32 s61, 0
	s_cbranch_scc1 .LBB0_222
	s_cmp_eq_u64 s[14:15], 0
	s_cbranch_scc1 .LBB0_222
	s_mov_b64 exec, s[54:55]
	v_add_u32_e32 v214, -2, v192
	v_mul_lo_u32 v214, v214, s53
	v_mov_b32_e32 v215, 0
	s_sub_i32 s32, s63, s45
	v_lshl_add_u64 v[212:213], v[154:155], 0, v[214:215]
	v_lshl_add_u64 v[216:217], v[156:157], 0, v[214:215]
	v_lshl_add_u64 v[214:215], v[212:213], 0, s[86:87]
	s_add_i32 m0, s32, 0x10000
	s_nop 0
	global_load_lds_dwordx4 v[214:215], off
	s_add_i32 m0, s32, 0x14000
	v_lshl_add_u64 v[214:215], v[212:213], 0, s[88:89]
	global_load_lds_dwordx4 v[216:217], off
	s_add_i32 m0, s32, 0x11000
	s_nop 0
	global_load_lds_dwordx4 v[214:215], off
	v_lshl_add_u64 v[214:215], v[216:217], 0, s[90:91]
	s_add_i32 m0, s32, 0x15000
	s_nop 0
	global_load_lds_dwordx4 v[214:215], off
	v_lshl_add_u64 v[214:215], v[212:213], 0, s[92:93]
	s_add_i32 m0, s32, 0x12000
	v_lshl_add_u64 v[212:213], v[212:213], 0, s[96:97]
	global_load_lds_dwordx4 v[214:215], off
	v_lshl_add_u64 v[214:215], v[216:217], 0, s[94:95]
	s_add_i32 m0, s32, 0x16000
	s_nop 0
	global_load_lds_dwordx4 v[214:215], off
	s_add_i32 m0, s32, 0x13000
	s_nop 0
	global_load_lds_dwordx4 v[212:213], off
	v_lshl_add_u64 v[212:213], v[216:217], 0, s[72:73]
	s_add_i32 m0, s32, 0x17000
	s_nop 0
	global_load_lds_dwordx4 v[212:213], off
	s_branch .LBB0_222

;     __device__ __forceinline__ void operator()(const f32x4 (&acc)[2][2][4][2], const Unit& u, int wr, int wc, int fr, int fq) const {
;         const int col0 = u.pn * BM + wc * 32 + 4 * fq;
; #pragma unroll
;         for (int ai = 0; ai < 2; ++ai)
; #pragma unroll
;             for (int m = 0; m < 4; ++m) { const int r = ai * HALF + wr * 64 + m * 16 + fr; const size_t off = (size_t)(u.pm * BM + r) * ldc + col0;
; #pragma unroll
;                 for (int bj = 0; bj < 2; ++bj)
; #pragma unroll
;                     for (int n = 0; n < 2; ++n) { const f32x4 bs = *(const f32x4*)(base + off + bj * HALF + n * 16); *(f32x4*)(out + off + bj * HALF + n * 16) = bs + acc[ai][bj][m][n]; } }
;     }
.LBB0_352:
	v_lshl_add_u32 v138, s56, 8, v140
	v_lshl_or_b32 v136, s55, 8, v142
	s_andn2_b64 vcc, exec, s[6:7]
	s_mov_b64 s[6:7], -1
	v_lshl_add_u32 v137, v138, 11, v136
	v_lshlrev_b32_e32 v137, 2, v137
	v_add_u32_e32 v139, 0x20000, v137
	v_add_u32_e32 v144, 0x40000, v137
	v_add_u32_e32 v145, 0x60000, v137
	v_add_u32_e32 v146, 0x100000, v137
	v_add_u32_e32 v152, 0x120000, v137
	v_add_u32_e32 v158, 0x140000, v137
	v_add_u32_e32 v159, 0x160000, v137
	global_load_dwordx4 v[148:151], v137, s[8:9]
	global_load_dwordx4 v[154:157], v137, s[8:9] offset:64
	global_load_dwordx4 v[162:165], v137, s[8:9] offset:512
	global_load_dwordx4 v[166:169], v137, s[8:9] offset:576
	global_load_dwordx4 v[186:189], v139, s[8:9]
	global_load_dwordx4 v[190:193], v139, s[8:9] offset:64
	global_load_dwordx4 v[194:197], v139, s[8:9] offset:512
	global_load_dwordx4 v[212:215], v139, s[8:9] offset:576
	global_load_dwordx4 v[220:223], v144, s[8:9]
	global_load_dwordx4 v[224:227], v144, s[8:9] offset:64
	global_load_dwordx4 v[228:231], v144, s[8:9] offset:512
	global_load_dwordx4 v[232:235], v144, s[8:9] offset:576
	global_load_dwordx4 v[236:239], v145, s[8:9]
	global_load_dwordx4 v[240:243], v145, s[8:9] offset:64
	global_load_dwordx4 v[244:247], v145, s[8:9] offset:512
	global_load_dwordx4 v[248:251], v145, s[8:9] offset:576
	s_waitcnt vmcnt(15)
	v_pk_add_f32 v[126:127], v[126:127], v[148:149]
	v_pk_add_f32 v[128:129], v[128:129], v[150:151]
	global_store_dwordx4 v137, v[126:129], s[12:13]
	global_load_dwordx4 v[148:151], v146, s[8:9]
	s_waitcnt vmcnt(16)
	v_pk_add_f32 v[122:123], v[122:123], v[154:155]
	v_pk_add_f32 v[124:125], v[124:125], v[156:157]
	global_store_dwordx4 v137, v[122:125], s[12:13] offset:64
	global_load_dwordx4 v[154:157], v146, s[8:9] offset:64
	s_waitcnt vmcnt(17)
	v_pk_add_f32 v[118:119], v[118:119], v[162:163]
	v_pk_add_f32 v[120:121], v[120:121], v[164:165]
	global_store_dwordx4 v137, v[118:121], s[12:13] offset:512
	global_load_dwordx4 v[162:165], v146, s[8:9] offset:512
	s_waitcnt vmcnt(18)
	v_pk_add_f32 v[106:107], v[106:107], v[166:167]
	v_pk_add_f32 v[108:109], v[108:109], v[168:169]
	global_store_dwordx4 v137, v[106:109], s[12:13] offset:576
	global_load_dwordx4 v[166:169], v146, s[8:9] offset:576
	s_waitcnt vmcnt(19)
	v_pk_add_f32 v[114:115], v[114:115], v[186:187]
	v_pk_add_f32 v[116:117], v[116:117], v[188:189]
	global_store_dwordx4 v139, v[114:117], s[12:13]
	global_load_dwordx4 v[186:189], v152, s[8:9]
	s_waitcnt vmcnt(20)
	v_pk_add_f32 v[110:111], v[110:111], v[190:191]
	v_pk_add_f32 v[112:113], v[112:113], v[192:193]
	global_store_dwordx4 v139, v[110:113], s[12:13] offset:64
	global_load_dwordx4 v[190:193], v152, s[8:9] offset:64
	s_waitcnt vmcnt(21)
	v_pk_add_f32 v[102:103], v[102:103], v[194:195]
	v_pk_add_f32 v[104:105], v[104:105], v[196:197]
	global_store_dwordx4 v139, v[102:105], s[12:13] offset:512
	global_load_dwordx4 v[194:197], v152, s[8:9] offset:512
	s_waitcnt vmcnt(22)
	v_pk_add_f32 v[90:91], v[90:91], v[212:213]
	v_pk_add_f32 v[92:93], v[92:93], v[214:215]
	global_store_dwordx4 v139, v[90:93], s[12:13] offset:576
	global_load_dwordx4 v[212:215], v152, s[8:9] offset:576
	s_waitcnt vmcnt(23)
	v_pk_add_f32 v[98:99], v[98:99], v[220:221]
	v_pk_add_f32 v[100:101], v[100:101], v[222:223]
	global_store_dwordx4 v144, v[98:101], s[12:13]
	global_load_dwordx4 v[220:223], v158, s[8:9]
	s_waitcnt vmcnt(24)
	v_pk_add_f32 v[94:95], v[94:95], v[224:225]
	v_pk_add_f32 v[96:97], v[96:97], v[226:227]
	global_store_dwordx4 v144, v[94:97], s[12:13] offset:64
	global_load_dwordx4 v[224:227], v158, s[8:9] offset:64
	s_waitcnt vmcnt(25)
	v_pk_add_f32 v[86:87], v[86:87], v[228:229]
	v_pk_add_f32 v[88:89], v[88:89], v[230:231]
	global_store_dwordx4 v144, v[86:89], s[12:13] offset:512
	global_load_dwordx4 v[228:231], v158, s[8:9] offset:512
	s_waitcnt vmcnt(26)
;     __device__ __forceinline__ void operator()(const f32x4 (&acc)[2][2][4][2], const Unit& u, int wr, int wc, int fr, int fq) const {
;         const int col0 = u.pn * BM + wc * 32 + 4 * fq;
; #pragma unroll
;         for (int ai = 0; ai < 2; ++ai)
; #pragma unroll
;             for (int m = 0; m < 4; ++m) { const int r = ai * HALF + wr * 64 + m * 16 + fr; const size_t off = (size_t)(u.pm * BM + r) * ldc + col0;
; #pragma unroll
;                 for (int bj = 0; bj < 2; ++bj)
; #pragma unroll
;                     for (int n = 0; n < 2; ++n) { const f32x4 bs = *(const f32x4*)(base + off + bj * HALF + n * 16); *(f32x4*)(out + off + bj * HALF + n * 16) = bs + acc[ai][bj][m][n]; } }
;     }
	v_pk_add_f32 v[74:75], v[74:75], v[232:233]
	v_pk_add_f32 v[76:77], v[76:77], v[234:235]
	global_store_dwordx4 v144, v[74:77], s[12:13] offset:576
	global_load_dwordx4 v[232:235], v158, s[8:9] offset:576
	s_waitcnt vmcnt(27)
	v_pk_add_f32 v[82:83], v[82:83], v[236:237]
	v_pk_add_f32 v[84:85], v[84:85], v[238:239]
	global_store_dwordx4 v145, v[82:85], s[12:13]
	global_load_dwordx4 v[236:239], v159, s[8:9]
	s_waitcnt vmcnt(28)
	v_pk_add_f32 v[78:79], v[78:79], v[240:241]
	v_pk_add_f32 v[80:81], v[80:81], v[242:243]
	global_store_dwordx4 v145, v[78:81], s[12:13] offset:64
	global_load_dwordx4 v[240:243], v159, s[8:9] offset:64
	s_waitcnt vmcnt(29)
	v_pk_add_f32 v[70:71], v[70:71], v[244:245]
	v_pk_add_f32 v[72:73], v[72:73], v[246:247]
	global_store_dwordx4 v145, v[70:73], s[12:13] offset:512
	global_load_dwordx4 v[244:247], v159, s[8:9] offset:512
	s_waitcnt vmcnt(30)
	v_pk_add_f32 v[66:67], v[66:67], v[248:249]
	v_pk_add_f32 v[68:69], v[68:69], v[250:251]
	global_store_dwordx4 v145, v[66:69], s[12:13] offset:576
	global_load_dwordx4 v[248:251], v159, s[8:9] offset:576
	s_waitcnt vmcnt(30)
	v_pk_add_f32 v[62:63], v[62:63], v[148:149]
	v_pk_add_f32 v[64:65], v[64:65], v[150:151]
	global_store_dwordx4 v146, v[62:65], s[12:13]
	s_waitcnt vmcnt(29)
	v_pk_add_f32 v[58:59], v[58:59], v[154:155]
	v_pk_add_f32 v[60:61], v[60:61], v[156:157]
	global_store_dwordx4 v146, v[58:61], s[12:13] offset:64
	s_waitcnt vmcnt(28)
	v_pk_add_f32 v[54:55], v[54:55], v[162:163]
	v_pk_add_f32 v[56:57], v[56:57], v[164:165]
	global_store_dwordx4 v146, v[54:57], s[12:13] offset:512
	s_waitcnt vmcnt(27)
	v_pk_add_f32 v[42:43], v[42:43], v[166:167]
	v_pk_add_f32 v[44:45], v[44:45], v[168:169]
	global_store_dwordx4 v146, v[42:45], s[12:13] offset:576
	s_waitcnt vmcnt(26)
	v_pk_add_f32 v[50:51], v[50:51], v[186:187]
	v_pk_add_f32 v[52:53], v[52:53], v[188:189]
	global_store_dwordx4 v152, v[50:53], s[12:13]
	s_waitcnt vmcnt(25)
	v_pk_add_f32 v[46:47], v[46:47], v[190:191]
	v_pk_add_f32 v[48:49], v[48:49], v[192:193]
	global_store_dwordx4 v152, v[46:49], s[12:13] offset:64
	s_waitcnt vmcnt(24)
	v_pk_add_f32 v[38:39], v[38:39], v[194:195]
	v_pk_add_f32 v[40:41], v[40:41], v[196:197]
	global_store_dwordx4 v152, v[38:41], s[12:13] offset:512
	s_waitcnt vmcnt(23)
	v_pk_add_f32 v[24:25], v[24:25], v[212:213]
	v_pk_add_f32 v[26:27], v[26:27], v[214:215]
	global_store_dwordx4 v152, v[24:27], s[12:13] offset:576
	s_waitcnt vmcnt(22)
	v_pk_add_f32 v[34:35], v[34:35], v[220:221]
	v_pk_add_f32 v[36:37], v[36:37], v[222:223]
	global_store_dwordx4 v158, v[34:37], s[12:13]
	s_waitcnt vmcnt(21)
	v_pk_add_f32 v[28:29], v[28:29], v[224:225]
	v_pk_add_f32 v[30:31], v[30:31], v[226:227]
	global_store_dwordx4 v158, v[28:31], s[12:13] offset:64
	s_waitcnt vmcnt(20)
	v_pk_add_f32 v[20:21], v[20:21], v[228:229]
	v_pk_add_f32 v[22:23], v[22:23], v[230:231]
	global_store_dwordx4 v158, v[20:23], s[12:13] offset:512
	s_waitcnt vmcnt(19)
	v_pk_add_f32 v[8:9], v[8:9], v[232:233]
	v_pk_add_f32 v[10:11], v[10:11], v[234:235]
	global_store_dwordx4 v158, v[8:11], s[12:13] offset:576
	s_waitcnt vmcnt(18)
	v_pk_add_f32 v[16:17], v[16:17], v[236:237]
	v_pk_add_f32 v[18:19], v[18:19], v[238:239]
	global_store_dwordx4 v159, v[16:19], s[12:13]
	s_waitcnt vmcnt(17)
	v_pk_add_f32 v[12:13], v[12:13], v[240:241]
	v_pk_add_f32 v[14:15], v[14:15], v[242:243]
	global_store_dwordx4 v159, v[12:15], s[12:13] offset:64
	s_waitcnt vmcnt(16)
	v_pk_add_f32 v[4:5], v[4:5], v[244:245]
	v_pk_add_f32 v[6:7], v[6:7], v[246:247]
	global_store_dwordx4 v159, v[4:7], s[12:13] offset:512
	s_waitcnt vmcnt(15)
	v_pk_add_f32 v[0:1], v[0:1], v[248:249]
	v_pk_add_f32 v[2:3], v[2:3], v[250:251]
	global_store_dwordx4 v159, v[0:3], s[12:13] offset:576
	s_cbranch_vccnz .LBB0_341
	s_andn2_b64 vcc, exec, s[10:11]
	s_cbranch_vccnz .LBB0_340
	s_barrier
	s_branch .LBB0_340

;     __device__ __forceinline__ void operator()(const f32x4 (&acc)[2][2][4][2], const Unit& u, int wr, int wc, int fr, int fq) const {
;         const int col0 = u.pn * BM + wc * 32 + 4 * fq;
; #pragma unroll
;         for (int ai = 0; ai < 2; ++ai)
; #pragma unroll
;             for (int m = 0; m < 4; ++m) { const int r = ai * HALF + wr * 64 + m * 16 + fr; const size_t off = (size_t)(u.pm * BM + r) * ldc + col0;
; #pragma unroll
;                 for (int bj = 0; bj < 2; ++bj)
; #pragma unroll
;                     for (int n = 0; n < 2; ++n) { const f32x4 bs = *(const f32x4*)(base + off + bj * HALF + n * 16); *(f32x4*)(out + off + bj * HALF + n * 16) = bs + acc[ai][bj][m][n]; } }
;     }
.LBB0_628:
	v_lshl_add_u32 v138, s56, 8, v140
	v_lshl_or_b32 v136, s55, 8, v142
	s_and_b64 vcc, exec, s[4:5]
	s_mov_b64 s[4:5], -1
	v_lshl_add_u32 v137, v138, 11, v136
	v_lshlrev_b32_e32 v137, 2, v137
	v_add_u32_e32 v139, 0x20000, v137
	v_add_u32_e32 v144, 0x40000, v137
	v_add_u32_e32 v145, 0x60000, v137
	v_add_u32_e32 v146, 0x100000, v137
	v_add_u32_e32 v152, 0x120000, v137
	v_add_u32_e32 v158, 0x140000, v137
	v_add_u32_e32 v159, 0x160000, v137
	global_load_dwordx4 v[148:151], v137, s[16:17]
	global_load_dwordx4 v[154:157], v137, s[16:17] offset:64
	global_load_dwordx4 v[162:165], v137, s[16:17] offset:512
	global_load_dwordx4 v[166:169], v137, s[16:17] offset:576
	global_load_dwordx4 v[186:189], v139, s[16:17]
	global_load_dwordx4 v[190:193], v139, s[16:17] offset:64
	global_load_dwordx4 v[194:197], v139, s[16:17] offset:512
	global_load_dwordx4 v[212:215], v139, s[16:17] offset:576
	global_load_dwordx4 v[220:223], v144, s[16:17]
	global_load_dwordx4 v[224:227], v144, s[16:17] offset:64
	global_load_dwordx4 v[228:231], v144, s[16:17] offset:512
	global_load_dwordx4 v[232:235], v144, s[16:17] offset:576
	global_load_dwordx4 v[236:239], v145, s[16:17]
	global_load_dwordx4 v[240:243], v145, s[16:17] offset:64
	global_load_dwordx4 v[244:247], v145, s[16:17] offset:512
	global_load_dwordx4 v[248:251], v145, s[16:17] offset:576
	s_waitcnt vmcnt(15)
	v_pk_add_f32 v[126:127], v[126:127], v[148:149]
	v_pk_add_f32 v[128:129], v[128:129], v[150:151]
	global_store_dwordx4 v137, v[126:129], s[18:19]
	global_load_dwordx4 v[148:151], v146, s[16:17]
	s_waitcnt vmcnt(16)
	v_pk_add_f32 v[122:123], v[122:123], v[154:155]
	v_pk_add_f32 v[124:125], v[124:125], v[156:157]
	global_store_dwordx4 v137, v[122:125], s[18:19] offset:64
	global_load_dwordx4 v[154:157], v146, s[16:17] offset:64
	s_waitcnt vmcnt(17)
	v_pk_add_f32 v[118:119], v[118:119], v[162:163]
	v_pk_add_f32 v[120:121], v[120:121], v[164:165]
	global_store_dwordx4 v137, v[118:121], s[18:19] offset:512
	global_load_dwordx4 v[162:165], v146, s[16:17] offset:512
	s_waitcnt vmcnt(18)
	v_pk_add_f32 v[106:107], v[106:107], v[166:167]
	v_pk_add_f32 v[108:109], v[108:109], v[168:169]
	global_store_dwordx4 v137, v[106:109], s[18:19] offset:576
	global_load_dwordx4 v[166:169], v146, s[16:17] offset:576
	s_waitcnt vmcnt(19)
	v_pk_add_f32 v[114:115], v[114:115], v[186:187]
	v_pk_add_f32 v[116:117], v[116:117], v[188:189]
	global_store_dwordx4 v139, v[114:117], s[18:19]
	global_load_dwordx4 v[186:189], v152, s[16:17]
	s_waitcnt vmcnt(20)
	v_pk_add_f32 v[110:111], v[110:111], v[190:191]
	v_pk_add_f32 v[112:113], v[112:113], v[192:193]
	global_store_dwordx4 v139, v[110:113], s[18:19] offset:64
	global_load_dwordx4 v[190:193], v152, s[16:17] offset:64
	s_waitcnt vmcnt(21)
	v_pk_add_f32 v[102:103], v[102:103], v[194:195]
	v_pk_add_f32 v[104:105], v[104:105], v[196:197]
	global_store_dwordx4 v139, v[102:105], s[18:19] offset:512
	global_load_dwordx4 v[194:197], v152, s[16:17] offset:512
	s_waitcnt vmcnt(22)
	v_pk_add_f32 v[90:91], v[90:91], v[212:213]
	v_pk_add_f32 v[92:93], v[92:93], v[214:215]
	global_store_dwordx4 v139, v[90:93], s[18:19] offset:576
	global_load_dwordx4 v[212:215], v152, s[16:17] offset:576
	s_waitcnt vmcnt(23)
	v_pk_add_f32 v[98:99], v[98:99], v[220:221]
	v_pk_add_f32 v[100:101], v[100:101], v[222:223]
	global_store_dwordx4 v144, v[98:101], s[18:19]
	global_load_dwordx4 v[220:223], v158, s[16:17]
	s_waitcnt vmcnt(24)
	v_pk_add_f32 v[94:95], v[94:95], v[224:225]
	v_pk_add_f32 v[96:97], v[96:97], v[226:227]
	global_store_dwordx4 v144, v[94:97], s[18:19] offset:64
	global_load_dwordx4 v[224:227], v158, s[16:17] offset:64
	s_waitcnt vmcnt(25)
	v_pk_add_f32 v[86:87], v[86:87], v[228:229]
	v_pk_add_f32 v[88:89], v[88:89], v[230:231]
	global_store_dwordx4 v144, v[86:89], s[18:19] offset:512
	global_load_dwordx4 v[228:231], v158, s[16:17] offset:512
	s_waitcnt vmcnt(26)
;     __device__ __forceinline__ void operator()(const f32x4 (&acc)[2][2][4][2], const Unit& u, int wr, int wc, int fr, int fq) const {
;         const int col0 = u.pn * BM + wc * 32 + 4 * fq;
; #pragma unroll
;         for (int ai = 0; ai < 2; ++ai)
; #pragma unroll
;             for (int m = 0; m < 4; ++m) { const int r = ai * HALF + wr * 64 + m * 16 + fr; const size_t off = (size_t)(u.pm * BM + r) * ldc + col0;
; #pragma unroll
;                 for (int bj = 0; bj < 2; ++bj)
; #pragma unroll
;                     for (int n = 0; n < 2; ++n) { const f32x4 bs = *(const f32x4*)(base + off + bj * HALF + n * 16); *(f32x4*)(out + off + bj * HALF + n * 16) = bs + acc[ai][bj][m][n]; } }
;     }
	v_pk_add_f32 v[74:75], v[74:75], v[232:233]
	v_pk_add_f32 v[76:77], v[76:77], v[234:235]
	global_store_dwordx4 v144, v[74:77], s[18:19] offset:576
	global_load_dwordx4 v[232:235], v158, s[16:17] offset:576
	s_waitcnt vmcnt(27)
	v_pk_add_f32 v[82:83], v[82:83], v[236:237]
	v_pk_add_f32 v[84:85], v[84:85], v[238:239]
	global_store_dwordx4 v145, v[82:85], s[18:19]
	global_load_dwordx4 v[236:239], v159, s[16:17]
	s_waitcnt vmcnt(28)
	v_pk_add_f32 v[78:79], v[78:79], v[240:241]
	v_pk_add_f32 v[80:81], v[80:81], v[242:243]
	global_store_dwordx4 v145, v[78:81], s[18:19] offset:64
	global_load_dwordx4 v[240:243], v159, s[16:17] offset:64
	s_waitcnt vmcnt(29)
	v_pk_add_f32 v[70:71], v[70:71], v[244:245]
	v_pk_add_f32 v[72:73], v[72:73], v[246:247]
	global_store_dwordx4 v145, v[70:73], s[18:19] offset:512
	global_load_dwordx4 v[244:247], v159, s[16:17] offset:512
	s_waitcnt vmcnt(30)
	v_pk_add_f32 v[66:67], v[66:67], v[248:249]
	v_pk_add_f32 v[68:69], v[68:69], v[250:251]
	global_store_dwordx4 v145, v[66:69], s[18:19] offset:576
	global_load_dwordx4 v[248:251], v159, s[16:17] offset:576
	s_waitcnt vmcnt(30)
	v_pk_add_f32 v[62:63], v[62:63], v[148:149]
	v_pk_add_f32 v[64:65], v[64:65], v[150:151]
	global_store_dwordx4 v146, v[62:65], s[18:19]
	s_waitcnt vmcnt(29)
	v_pk_add_f32 v[58:59], v[58:59], v[154:155]
	v_pk_add_f32 v[60:61], v[60:61], v[156:157]
	global_store_dwordx4 v146, v[58:61], s[18:19] offset:64
	s_waitcnt vmcnt(28)
	v_pk_add_f32 v[54:55], v[54:55], v[162:163]
	v_pk_add_f32 v[56:57], v[56:57], v[164:165]
	global_store_dwordx4 v146, v[54:57], s[18:19] offset:512
	s_waitcnt vmcnt(27)
	v_pk_add_f32 v[42:43], v[42:43], v[166:167]
	v_pk_add_f32 v[44:45], v[44:45], v[168:169]
	global_store_dwordx4 v146, v[42:45], s[18:19] offset:576
	s_waitcnt vmcnt(26)
	v_pk_add_f32 v[50:51], v[50:51], v[186:187]
	v_pk_add_f32 v[52:53], v[52:53], v[188:189]
	global_store_dwordx4 v152, v[50:53], s[18:19]
	s_waitcnt vmcnt(25)
	v_pk_add_f32 v[46:47], v[46:47], v[190:191]
	v_pk_add_f32 v[48:49], v[48:49], v[192:193]
	global_store_dwordx4 v152, v[46:49], s[18:19] offset:64
	s_waitcnt vmcnt(24)
	v_pk_add_f32 v[38:39], v[38:39], v[194:195]
	v_pk_add_f32 v[40:41], v[40:41], v[196:197]
	global_store_dwordx4 v152, v[38:41], s[18:19] offset:512
	s_waitcnt vmcnt(23)
	v_pk_add_f32 v[24:25], v[24:25], v[212:213]
	v_pk_add_f32 v[26:27], v[26:27], v[214:215]
	global_store_dwordx4 v152, v[24:27], s[18:19] offset:576
	s_waitcnt vmcnt(22)
	v_pk_add_f32 v[34:35], v[34:35], v[220:221]
	v_pk_add_f32 v[36:37], v[36:37], v[222:223]
	global_store_dwordx4 v158, v[34:37], s[18:19]
	s_waitcnt vmcnt(21)
	v_pk_add_f32 v[28:29], v[28:29], v[224:225]
	v_pk_add_f32 v[30:31], v[30:31], v[226:227]
	global_store_dwordx4 v158, v[28:31], s[18:19] offset:64
	s_waitcnt vmcnt(20)
	v_pk_add_f32 v[20:21], v[20:21], v[228:229]
	v_pk_add_f32 v[22:23], v[22:23], v[230:231]
	global_store_dwordx4 v158, v[20:23], s[18:19] offset:512
	s_waitcnt vmcnt(19)
	v_pk_add_f32 v[8:9], v[8:9], v[232:233]
	v_pk_add_f32 v[10:11], v[10:11], v[234:235]
	global_store_dwordx4 v158, v[8:11], s[18:19] offset:576
	s_waitcnt vmcnt(18)
	v_pk_add_f32 v[16:17], v[16:17], v[236:237]
	v_pk_add_f32 v[18:19], v[18:19], v[238:239]
	global_store_dwordx4 v159, v[16:19], s[18:19]
	s_waitcnt vmcnt(17)
	v_pk_add_f32 v[12:13], v[12:13], v[240:241]
	v_pk_add_f32 v[14:15], v[14:15], v[242:243]
	global_store_dwordx4 v159, v[12:15], s[18:19] offset:64
	s_waitcnt vmcnt(16)
	v_pk_add_f32 v[4:5], v[4:5], v[244:245]
	v_pk_add_f32 v[6:7], v[6:7], v[246:247]
	global_store_dwordx4 v159, v[4:7], s[18:19] offset:512
	s_waitcnt vmcnt(15)
	v_pk_add_f32 v[0:1], v[0:1], v[248:249]
	v_pk_add_f32 v[2:3], v[2:3], v[250:251]
	global_store_dwordx4 v159, v[0:3], s[18:19] offset:576
	s_cbranch_vccnz .LBB0_613
	s_andn2_b64 vcc, exec, s[12:13]
	s_cbranch_vccnz .LBB0_612
	s_barrier
	s_branch .LBB0_612
